# same as previous (pooled dynamic tile pairs in P0) with the loop safety cap raised above the pool size so a claimed pair can never be dropped
# baseline (speedup 1.0000x reference)
.LBB0_74:
	s_waitcnt vmcnt(39)
	v_pk_mul_f32 v[84:85], v[2:3], v[70:71] op_sel_hi:[1,0]
	ds_write2_b32 v75, v84, v85 offset1:1
	v_pk_mul_f32 v[84:85], v[4:5], v[70:71] op_sel_hi:[1,0]
	ds_write2_b32 v75, v84, v85 offset0:2 offset1:3
	s_waitcnt vmcnt(38)
	v_pk_mul_f32 v[84:85], v[6:7], v[70:71] op_sel_hi:[1,0]
	v_accvgpr_read_b32 v0, a3
	ds_write2_b32 v0, v84, v85 offset1:1
	v_pk_mul_f32 v[84:85], v[8:9], v[70:71] op_sel_hi:[1,0]
	v_accvgpr_read_b32 v0, a5
	ds_write2_b32 v0, v84, v85 offset1:1
	s_waitcnt vmcnt(37)
	v_pk_mul_f32 v[84:85], v[10:11], v[70:71] op_sel_hi:[1,0]
	v_accvgpr_read_b32 v0, a7
	ds_write2_b32 v0, v84, v85 offset1:1
	v_pk_mul_f32 v[84:85], v[12:13], v[70:71] op_sel_hi:[1,0]
	v_accvgpr_read_b32 v0, a9
	ds_write2_b32 v0, v84, v85 offset1:1
	s_waitcnt vmcnt(36)
	v_pk_mul_f32 v[84:85], v[14:15], v[70:71] op_sel_hi:[1,0]
	v_accvgpr_read_b32 v0, a10
	ds_write2_b32 v0, v84, v85 offset1:1
	v_pk_mul_f32 v[84:85], v[16:17], v[70:71] op_sel_hi:[1,0]
	v_accvgpr_read_b32 v0, a11
	ds_write2_b32 v0, v84, v85 offset1:1
	s_waitcnt vmcnt(35)
	v_pk_mul_f32 v[84:85], v[18:19], v[70:71] op_sel_hi:[1,0]
	v_accvgpr_read_b32 v0, a12
	ds_write2_b32 v0, v84, v85 offset1:1
	v_pk_mul_f32 v[84:85], v[20:21], v[70:71] op_sel_hi:[1,0]
	v_accvgpr_read_b32 v0, a13
	ds_write2_b32 v0, v84, v85 offset1:1
	s_waitcnt vmcnt(34)
	v_pk_mul_f32 v[84:85], v[22:23], v[70:71] op_sel_hi:[1,0]
	v_accvgpr_read_b32 v0, a18
	ds_write2_b32 v0, v84, v85 offset1:1
	v_pk_mul_f32 v[84:85], v[24:25], v[70:71] op_sel_hi:[1,0]
	v_accvgpr_read_b32 v0, a19
	ds_write2_b32 v0, v84, v85 offset1:1
	s_waitcnt vmcnt(33)
	v_pk_mul_f32 v[84:85], v[26:27], v[70:71] op_sel_hi:[1,0]
	v_accvgpr_read_b32 v0, a20
	ds_write2_b32 v0, v84, v85 offset1:1
	v_pk_mul_f32 v[84:85], v[28:29], v[70:71] op_sel_hi:[1,0]
	v_accvgpr_read_b32 v0, a21
	ds_write2_b32 v0, v84, v85 offset1:1
	s_waitcnt vmcnt(32)
	v_pk_mul_f32 v[84:85], v[30:31], v[70:71] op_sel_hi:[1,0]
	v_accvgpr_read_b32 v0, a22
	ds_write2_b32 v0, v84, v85 offset1:1
	v_pk_mul_f32 v[84:85], v[32:33], v[70:71] op_sel_hi:[1,0]
	v_accvgpr_read_b32 v0, a23
	ds_write2_b32 v0, v84, v85 offset1:1
	s_waitcnt vmcnt(31)
	v_pk_mul_f32 v[84:85], v[34:35], v[70:71] op_sel_hi:[1,0]
	v_accvgpr_read_b32 v0, a24
	ds_write2_b32 v0, v84, v85 offset1:1
	v_pk_mul_f32 v[84:85], v[36:37], v[70:71] op_sel_hi:[1,0]
	v_accvgpr_read_b32 v0, a25
	ds_write2_b32 v0, v84, v85 offset1:1
	s_waitcnt vmcnt(30)
	v_pk_mul_f32 v[84:85], v[38:39], v[70:71] op_sel_hi:[1,0]
	v_accvgpr_read_b32 v0, a30
	ds_write2_b32 v0, v84, v85 offset1:1
	v_pk_mul_f32 v[84:85], v[40:41], v[70:71] op_sel_hi:[1,0]
	v_accvgpr_read_b32 v0, a31
	ds_write2_b32 v0, v84, v85 offset1:1
	s_waitcnt vmcnt(29)
	v_pk_mul_f32 v[84:85], v[42:43], v[70:71] op_sel_hi:[1,0]
	v_accvgpr_read_b32 v0, a32
	ds_write2_b32 v0, v84, v85 offset1:1
	v_pk_mul_f32 v[84:85], v[44:45], v[70:71] op_sel_hi:[1,0]
	v_accvgpr_read_b32 v0, a33
	ds_write2_b32 v0, v84, v85 offset1:1
	s_waitcnt vmcnt(28)
	v_pk_mul_f32 v[84:85], v[46:47], v[70:71] op_sel_hi:[1,0]
	v_accvgpr_read_b32 v0, a34
	ds_write2_b32 v0, v84, v85 offset1:1
	v_pk_mul_f32 v[84:85], v[48:49], v[70:71] op_sel_hi:[1,0]
	v_accvgpr_read_b32 v0, a35
	ds_write2_b32 v0, v84, v85 offset1:1
	s_waitcnt vmcnt(27)
	v_pk_mul_f32 v[84:85], v[50:51], v[70:71] op_sel_hi:[1,0]
	v_accvgpr_read_b32 v0, a40
	ds_write2_b32 v0, v84, v85 offset1:1
	v_pk_mul_f32 v[84:85], v[52:53], v[70:71] op_sel_hi:[1,0]
	v_accvgpr_read_b32 v0, a41
	ds_write2_b32 v0, v84, v85 offset1:1
	s_waitcnt vmcnt(26)
	v_pk_mul_f32 v[84:85], v[54:55], v[70:71] op_sel_hi:[1,0]
	v_accvgpr_read_b32 v0, a42
	ds_write2_b32 v0, v84, v85 offset1:1
	v_pk_mul_f32 v[84:85], v[56:57], v[70:71] op_sel_hi:[1,0]
	v_accvgpr_read_b32 v0, a43
	ds_write2_b32 v0, v84, v85 offset1:1
	s_waitcnt vmcnt(25)
	v_pk_mul_f32 v[84:85], v[58:59], v[70:71] op_sel_hi:[1,0]
	v_accvgpr_read_b32 v0, a44
	ds_write2_b32 v0, v84, v85 offset1:1
	v_pk_mul_f32 v[84:85], v[60:61], v[70:71] op_sel_hi:[1,0]
	v_accvgpr_read_b32 v0, a45
	ds_write2_b32 v0, v84, v85 offset1:1
	s_waitcnt vmcnt(24)
	v_pk_mul_f32 v[84:85], v[62:63], v[70:71] op_sel_hi:[1,0]
	v_accvgpr_read_b32 v0, a50
	s_cmpk_lg_u32 s80, 0x800
	s_cbranch_scc1 .Lp0d_static
	v_accvgpr_read_b32 v91, a76
	s_nop 0
	v_readfirstlane_b32 s41, v91
	s_and_b32 s45, s41, 7
	s_lshl_b32 s45, s45, 3
	s_or_b32 s45, s45, s44
	s_bfe_u32 s36, s41, 0x30003
	s_lshl_b32 s36, s36, 8
	s_or_b32 s45, s45, s36
	s_lshr_b32 s41, s41, 6
	s_add_i32 s41, s41, 1
	s_lshl_b32 s41, s41, 12
	s_add_i32 s41, s41, s45
	s_cmpk_gt_u32 s39, 0x300
	s_cselect_b32 s41, 0xc000, s41
	v_mov_b32_e32 v91, s41
	s_mov_b64 exec, 1
	s_nop 0
	global_atomic_add a76, v1, a77, s[42:43] sc0
	s_mov_b64 exec, -1
	s_branch .Lp0d_join
